# v26 + SwiGLU hidden-activation stores use the default cache policy instead of nontemporal
# speedup vs baseline: 1.0029x; 1.0029x over previous
; DI unsigned pk2(float lo, float hi) { f32x2 v = {lo, hi}; bf16x2_t b = __builtin_convertvector(v, bf16x2_t); return __builtin_bit_cast(unsigned, b); }
;     DI void operator()(const f32x4 (&acc)[2][2][4][2], const Unit& u, int wr, int wc, int fr, int fq) const {
;     ...
;                 bf16_t* rowp = O + (size_t)(row0 + ai * HALF + m * 16) * DFF + col0;
;                 const f32x4 g0 = acc[ai][0][m][0], g1 = acc[ai][0][m][1], u0 = acc[ai][1][m][0], u1 = acc[ai][1][m][1];
;                 u32x4 w;
;                 f32x4 e0, e1;
; #pragma unroll
;                 for (int e = 0; e < 4; ++e) { e0[e] = __builtin_amdgcn_exp2f(-g0[e]); e1[e] = __builtin_amdgcn_exp2f(-g1[e]); }
;                 e0 = e0 + 1.0f; e1 = e1 + 1.0f;
; #pragma unroll
;                 for (int e = 0; e < 4; ++e) { e0[e] = __builtin_amdgcn_rcpf(e0[e]); e1[e] = __builtin_amdgcn_rcpf(e1[e]); }
;                 const f32x4 r0 = g0 * u0 * e0, r1 = g1 * u1 * e1;
;                 w.x = pk2(r0[0], r0[1]); w.y = pk2(r0[2], r0[3]); w.z = pk2(r1[0], r1[1]); w.w = pk2(r1[2], r1[3]);
;                 __builtin_nontemporal_store(w, (u32x4*)rowp);
.LBB0_516:
	v_exp_f32_e64 v150, -v126
	v_exp_f32_e64 v152, -v122
	v_exp_f32_e64 v151, -v127
	v_exp_f32_e64 v154, -v128
	v_exp_f32_e64 v155, -v129
	v_exp_f32_e64 v156, -v124
	v_exp_f32_e64 v157, -v125
	v_exp_f32_e64 v153, -v123
	v_pk_add_f32 v[154:155], v[154:155], 1.0 op_sel_hi:[1,0]
	v_pk_add_f32 v[150:151], v[150:151], 1.0 op_sel_hi:[1,0]
	v_pk_add_f32 v[156:157], v[156:157], 1.0 op_sel_hi:[1,0]
	v_pk_add_f32 v[152:153], v[152:153], 1.0 op_sel_hi:[1,0]
	v_rcp_f32_e32 v150, v150
	v_rcp_f32_e32 v152, v152
	v_rcp_f32_e32 v151, v151
	v_rcp_f32_e32 v153, v153
	v_rcp_f32_e32 v154, v154
	v_rcp_f32_e32 v156, v156
	v_rcp_f32_e32 v155, v155
	v_rcp_f32_e32 v157, v157
	v_lshl_or_b32 v142, s33, 7, v146
	v_lshl_add_u32 v158, s72, 8, v144
	v_ashrrev_i32_e32 v143, 31, v142
	v_mov_b64_e32 v[140:141], s[62:63]
	v_pk_mul_f32 v[120:121], v[128:129], v[120:121]
	v_pk_mul_f32 v[118:119], v[126:127], v[118:119]
	v_pk_mul_f32 v[116:117], v[124:125], v[116:117]
	v_pk_mul_f32 v[114:115], v[122:123], v[114:115]
	v_mad_i64_i32 v[148:149], s[40:41], v158, s38, v[140:141]
	v_lshlrev_b64 v[142:143], 1, v[142:143]
	v_pk_mul_f32 v[120:121], v[154:155], v[120:121]
	v_pk_mul_f32 v[118:119], v[150:151], v[118:119]
	v_pk_mul_f32 v[122:123], v[156:157], v[116:117]
	v_pk_mul_f32 v[116:117], v[152:153], v[114:115]
	v_lshl_add_u64 v[148:149], v[148:149], 0, v[142:143]
	v_cvt_pk_bf16_f32 v114, v118, v119
	v_cvt_pk_bf16_f32 v115, v120, v121
	v_cvt_pk_bf16_f32 v116, v116, v117
	v_cvt_pk_bf16_f32 v117, v122, v123
	global_store_dwordx4 v[148:149], v[114:117], off
	v_exp_f32_e64 v118, -v106
	v_exp_f32_e64 v120, -v112
	v_exp_f32_e64 v116, -v110
	v_exp_f32_e64 v117, -v111
	v_exp_f32_e64 v121, -v113
	v_exp_f32_e64 v122, -v108
	v_exp_f32_e64 v123, -v109
	v_exp_f32_e64 v119, -v107
	v_pk_add_f32 v[120:121], v[120:121], 1.0 op_sel_hi:[1,0]
	v_pk_add_f32 v[116:117], v[116:117], 1.0 op_sel_hi:[1,0]
	v_pk_add_f32 v[122:123], v[122:123], 1.0 op_sel_hi:[1,0]
	v_pk_add_f32 v[118:119], v[118:119], 1.0 op_sel_hi:[1,0]
	v_rcp_f32_e32 v116, v116
	v_rcp_f32_e32 v118, v118
	v_rcp_f32_e32 v117, v117
	v_rcp_f32_e32 v119, v119
	v_rcp_f32_e32 v120, v120
	v_rcp_f32_e32 v122, v122
	v_rcp_f32_e32 v121, v121
	v_rcp_f32_e32 v123, v123
	v_or_b32_e32 v114, 16, v158
	v_pk_mul_f32 v[104:105], v[112:113], v[104:105]
	v_pk_mul_f32 v[102:103], v[110:111], v[102:103]
	v_pk_mul_f32 v[100:101], v[108:109], v[100:101]
	v_pk_mul_f32 v[98:99], v[106:107], v[98:99]
	v_mad_i64_i32 v[114:115], s[40:41], v114, s38, v[140:141]
	v_pk_mul_f32 v[104:105], v[120:121], v[104:105]
	v_pk_mul_f32 v[102:103], v[116:117], v[102:103]
	v_pk_mul_f32 v[106:107], v[122:123], v[100:101]
	v_pk_mul_f32 v[100:101], v[118:119], v[98:99]
	v_lshl_add_u64 v[114:115], v[114:115], 0, v[142:143]
	v_cvt_pk_bf16_f32 v98, v102, v103
	v_cvt_pk_bf16_f32 v99, v104, v105
	v_cvt_pk_bf16_f32 v100, v100, v101
	v_cvt_pk_bf16_f32 v101, v106, v107
	global_store_dwordx4 v[114:115], v[98:101], off
	v_exp_f32_e64 v102, -v90
	v_exp_f32_e64 v104, -v96
	v_exp_f32_e64 v100, -v94
	v_exp_f32_e64 v101, -v95
	v_exp_f32_e64 v105, -v97
	v_exp_f32_e64 v106, -v92
	v_exp_f32_e64 v107, -v93
	v_exp_f32_e64 v103, -v91
	v_pk_add_f32 v[104:105], v[104:105], 1.0 op_sel_hi:[1,0]
	v_pk_add_f32 v[100:101], v[100:101], 1.0 op_sel_hi:[1,0]
	v_pk_add_f32 v[106:107], v[106:107], 1.0 op_sel_hi:[1,0]
	v_pk_add_f32 v[102:103], v[102:103], 1.0 op_sel_hi:[1,0]
	v_rcp_f32_e32 v100, v100
	v_rcp_f32_e32 v102, v102
	v_rcp_f32_e32 v101, v101
	v_rcp_f32_e32 v103, v103
	v_rcp_f32_e32 v104, v104
	v_rcp_f32_e32 v106, v106
	v_rcp_f32_e32 v105, v105
	v_rcp_f32_e32 v107, v107
	v_or_b32_e32 v98, 32, v158
	v_pk_mul_f32 v[88:89], v[96:97], v[88:89]
	v_pk_mul_f32 v[86:87], v[94:95], v[86:87]
	v_pk_mul_f32 v[84:85], v[92:93], v[84:85]
	v_pk_mul_f32 v[82:83], v[90:91], v[82:83]
	v_mad_i64_i32 v[98:99], s[40:41], v98, s38, v[140:141]
	v_pk_mul_f32 v[88:89], v[104:105], v[88:89]
	v_pk_mul_f32 v[86:87], v[100:101], v[86:87]
	v_pk_mul_f32 v[90:91], v[106:107], v[84:85]
	v_pk_mul_f32 v[84:85], v[102:103], v[82:83]
	v_lshl_add_u64 v[98:99], v[98:99], 0, v[142:143]
	v_cvt_pk_bf16_f32 v82, v86, v87
	v_cvt_pk_bf16_f32 v83, v88, v89
	v_cvt_pk_bf16_f32 v84, v84, v85
	v_cvt_pk_bf16_f32 v85, v90, v91
	global_store_dwordx4 v[98:99], v[82:85], off
	v_exp_f32_e64 v86, -v74
	v_exp_f32_e64 v88, -v80
	v_exp_f32_e64 v84, -v78
	v_exp_f32_e64 v85, -v79
	v_exp_f32_e64 v89, -v81
	v_exp_f32_e64 v90, -v76
	v_exp_f32_e64 v91, -v77
	v_exp_f32_e64 v87, -v75
	v_pk_add_f32 v[88:89], v[88:89], 1.0 op_sel_hi:[1,0]
	v_pk_add_f32 v[84:85], v[84:85], 1.0 op_sel_hi:[1,0]
	v_pk_add_f32 v[90:91], v[90:91], 1.0 op_sel_hi:[1,0]
	v_pk_add_f32 v[86:87], v[86:87], 1.0 op_sel_hi:[1,0]
	v_rcp_f32_e32 v84, v84
	v_rcp_f32_e32 v86, v86
	v_rcp_f32_e32 v85, v85
	v_rcp_f32_e32 v87, v87
	v_rcp_f32_e32 v88, v88
	v_rcp_f32_e32 v90, v90
	v_rcp_f32_e32 v89, v89
	v_rcp_f32_e32 v91, v91
	v_or_b32_e32 v82, 48, v158
	v_pk_mul_f32 v[72:73], v[80:81], v[72:73]
	v_pk_mul_f32 v[70:71], v[78:79], v[70:71]
	v_pk_mul_f32 v[68:69], v[76:77], v[68:69]
	v_pk_mul_f32 v[66:67], v[74:75], v[66:67]
	v_mad_i64_i32 v[82:83], s[40:41], v82, s38, v[140:141]
	v_pk_mul_f32 v[72:73], v[88:89], v[72:73]
	v_pk_mul_f32 v[70:71], v[84:85], v[70:71]
	v_pk_mul_f32 v[74:75], v[90:91], v[68:69]
	v_pk_mul_f32 v[68:69], v[86:87], v[66:67]
	v_lshl_add_u64 v[82:83], v[82:83], 0, v[142:143]
	v_cvt_pk_bf16_f32 v66, v70, v71
; DI unsigned pk2(float lo, float hi) { f32x2 v = {lo, hi}; bf16x2_t b = __builtin_convertvector(v, bf16x2_t); return __builtin_bit_cast(unsigned, b); }
; #define PG8_BAR __builtin_amdgcn_s_barrier()
; template <class Epi>
; DI void gemm_phase(LAS unsigned char* lds, int tid, const Gemm g, const Order& S, const Epi& E) {
;     ...
;         if (!has_next) break;
; #pragma unroll
;         for (int a = 0; a < 2; ++a)
; #pragma unroll
;             for (int b = 0; b < 2; ++b)
; #pragma unroll
;                 for (int m = 0; m < 4; ++m)
; #pragma unroll
;                     for (int n = 0; n < 2; ++n) acc[a][b][m][n] = (f32x4){0.f, 0.f, 0.f, 0.f};
;         cur = nxt; cA = nA; cB = nB; ++ui;
;         if (wr == 1) PG8_BAR;
;     DI void operator()(const f32x4 (&acc)[2][2][4][2], const Unit& u, int wr, int wc, int fr, int fq) const {
;     ...
;                 bf16_t* rowp = O + (size_t)(row0 + ai * HALF + m * 16) * DFF + col0;
;                 const f32x4 g0 = acc[ai][0][m][0], g1 = acc[ai][0][m][1], u0 = acc[ai][1][m][0], u1 = acc[ai][1][m][1];
;                 u32x4 w;
;                 f32x4 e0, e1;
; #pragma unroll
;                 for (int e = 0; e < 4; ++e) { e0[e] = __builtin_amdgcn_exp2f(-g0[e]); e1[e] = __builtin_amdgcn_exp2f(-g1[e]); }
;                 e0 = e0 + 1.0f; e1 = e1 + 1.0f;
; #pragma unroll
;                 for (int e = 0; e < 4; ++e) { e0[e] = __builtin_amdgcn_rcpf(e0[e]); e1[e] = __builtin_amdgcn_rcpf(e1[e]); }
;                 const f32x4 r0 = g0 * u0 * e0, r1 = g1 * u1 * e1;
;                 w.x = pk2(r0[0], r0[1]); w.y = pk2(r0[2], r0[3]); w.z = pk2(r1[0], r1[1]); w.w = pk2(r1[2], r1[3]);
;                 __builtin_nontemporal_store(w, (u32x4*)rowp);
	v_cvt_pk_bf16_f32 v67, v72, v73
	v_cvt_pk_bf16_f32 v68, v68, v69
	v_cvt_pk_bf16_f32 v69, v74, v75
	global_store_dwordx4 v[82:83], v[66:69], off
	v_exp_f32_e64 v70, -v58
	v_exp_f32_e64 v72, -v64
	v_exp_f32_e64 v68, -v62
	v_exp_f32_e64 v69, -v63
	v_exp_f32_e64 v73, -v65
	v_exp_f32_e64 v74, -v60
	v_exp_f32_e64 v75, -v61
	v_exp_f32_e64 v71, -v59
	v_pk_add_f32 v[72:73], v[72:73], 1.0 op_sel_hi:[1,0]
	v_pk_add_f32 v[68:69], v[68:69], 1.0 op_sel_hi:[1,0]
	v_pk_add_f32 v[74:75], v[74:75], 1.0 op_sel_hi:[1,0]
	v_pk_add_f32 v[70:71], v[70:71], 1.0 op_sel_hi:[1,0]
	v_rcp_f32_e32 v68, v68
	v_rcp_f32_e32 v70, v70
	v_rcp_f32_e32 v69, v69
	v_rcp_f32_e32 v71, v71
	v_rcp_f32_e32 v72, v72
	v_rcp_f32_e32 v74, v74
	v_rcp_f32_e32 v73, v73
	v_rcp_f32_e32 v75, v75
	v_add_u32_e32 v66, 0x80, v158
	v_pk_mul_f32 v[56:57], v[64:65], v[56:57]
	v_pk_mul_f32 v[54:55], v[62:63], v[54:55]
	v_pk_mul_f32 v[52:53], v[60:61], v[52:53]
	v_pk_mul_f32 v[50:51], v[58:59], v[50:51]
	v_mad_i64_i32 v[66:67], s[40:41], v66, s38, v[140:141]
	v_pk_mul_f32 v[56:57], v[72:73], v[56:57]
	v_pk_mul_f32 v[54:55], v[68:69], v[54:55]
	v_pk_mul_f32 v[58:59], v[74:75], v[52:53]
	v_pk_mul_f32 v[52:53], v[70:71], v[50:51]
	v_lshl_add_u64 v[66:67], v[66:67], 0, v[142:143]
	v_cvt_pk_bf16_f32 v50, v54, v55
	v_cvt_pk_bf16_f32 v51, v56, v57
	v_cvt_pk_bf16_f32 v52, v52, v53
	v_cvt_pk_bf16_f32 v53, v58, v59
	global_store_dwordx4 v[66:67], v[50:53], off
	v_exp_f32_e64 v54, -v42
	v_exp_f32_e64 v56, -v48
	v_exp_f32_e64 v52, -v46
	v_exp_f32_e64 v53, -v47
	v_exp_f32_e64 v57, -v49
	v_exp_f32_e64 v58, -v44
	v_exp_f32_e64 v59, -v45
	v_exp_f32_e64 v55, -v43
	v_pk_add_f32 v[56:57], v[56:57], 1.0 op_sel_hi:[1,0]
	v_pk_add_f32 v[52:53], v[52:53], 1.0 op_sel_hi:[1,0]
	v_pk_add_f32 v[58:59], v[58:59], 1.0 op_sel_hi:[1,0]
	v_pk_add_f32 v[54:55], v[54:55], 1.0 op_sel_hi:[1,0]
	v_rcp_f32_e32 v52, v52
	v_rcp_f32_e32 v54, v54
	v_rcp_f32_e32 v53, v53
	v_rcp_f32_e32 v55, v55
	v_rcp_f32_e32 v56, v56
	v_rcp_f32_e32 v58, v58
	v_rcp_f32_e32 v57, v57
	v_rcp_f32_e32 v59, v59
	v_add_u32_e32 v50, 0x90, v158
	v_pk_mul_f32 v[40:41], v[48:49], v[40:41]
	v_pk_mul_f32 v[38:39], v[46:47], v[38:39]
	v_pk_mul_f32 v[36:37], v[44:45], v[36:37]
	v_pk_mul_f32 v[34:35], v[42:43], v[34:35]
	v_mad_i64_i32 v[50:51], s[40:41], v50, s38, v[140:141]
	v_pk_mul_f32 v[40:41], v[56:57], v[40:41]
	v_pk_mul_f32 v[38:39], v[52:53], v[38:39]
	v_pk_mul_f32 v[42:43], v[58:59], v[36:37]
	v_pk_mul_f32 v[36:37], v[54:55], v[34:35]
	v_lshl_add_u64 v[50:51], v[50:51], 0, v[142:143]
	v_cvt_pk_bf16_f32 v34, v38, v39
	v_cvt_pk_bf16_f32 v35, v40, v41
	v_cvt_pk_bf16_f32 v36, v36, v37
	v_cvt_pk_bf16_f32 v37, v42, v43
	global_store_dwordx4 v[50:51], v[34:37], off
	v_exp_f32_e64 v38, -v26
	v_exp_f32_e64 v40, -v32
	v_exp_f32_e64 v36, -v30
	v_exp_f32_e64 v37, -v31
	v_exp_f32_e64 v41, -v33
	v_exp_f32_e64 v42, -v28
	v_exp_f32_e64 v43, -v29
	v_exp_f32_e64 v39, -v27
	v_pk_add_f32 v[40:41], v[40:41], 1.0 op_sel_hi:[1,0]
	v_pk_add_f32 v[36:37], v[36:37], 1.0 op_sel_hi:[1,0]
	v_pk_add_f32 v[42:43], v[42:43], 1.0 op_sel_hi:[1,0]
	v_pk_add_f32 v[38:39], v[38:39], 1.0 op_sel_hi:[1,0]
	v_rcp_f32_e32 v36, v36
	v_rcp_f32_e32 v38, v38
	v_rcp_f32_e32 v37, v37
	v_rcp_f32_e32 v39, v39
	v_rcp_f32_e32 v40, v40
	v_rcp_f32_e32 v42, v42
	v_rcp_f32_e32 v41, v41
	v_rcp_f32_e32 v43, v43
	v_add_u32_e32 v34, 0xa0, v158
	v_pk_mul_f32 v[24:25], v[32:33], v[24:25]
	v_pk_mul_f32 v[22:23], v[30:31], v[22:23]
	v_pk_mul_f32 v[20:21], v[28:29], v[20:21]
	v_pk_mul_f32 v[18:19], v[26:27], v[18:19]
	v_mad_i64_i32 v[34:35], s[40:41], v34, s38, v[140:141]
	v_pk_mul_f32 v[24:25], v[40:41], v[24:25]
	v_pk_mul_f32 v[22:23], v[36:37], v[22:23]
	v_pk_mul_f32 v[26:27], v[42:43], v[20:21]
	v_pk_mul_f32 v[20:21], v[38:39], v[18:19]
	v_lshl_add_u64 v[34:35], v[34:35], 0, v[142:143]
	v_cvt_pk_bf16_f32 v18, v22, v23
	v_cvt_pk_bf16_f32 v19, v24, v25
	v_cvt_pk_bf16_f32 v20, v20, v21
	v_cvt_pk_bf16_f32 v21, v26, v27
	global_store_dwordx4 v[34:35], v[18:21], off
	v_exp_f32_e64 v22, -v10
	v_exp_f32_e64 v24, -v16
	v_exp_f32_e64 v20, -v14
	v_exp_f32_e64 v21, -v15
	v_exp_f32_e64 v25, -v17
	v_exp_f32_e64 v26, -v12
	v_exp_f32_e64 v27, -v13
	v_exp_f32_e64 v23, -v11
	v_pk_add_f32 v[24:25], v[24:25], 1.0 op_sel_hi:[1,0]
	v_pk_add_f32 v[20:21], v[20:21], 1.0 op_sel_hi:[1,0]
	v_pk_add_f32 v[26:27], v[26:27], 1.0 op_sel_hi:[1,0]
	v_pk_add_f32 v[22:23], v[22:23], 1.0 op_sel_hi:[1,0]
	v_rcp_f32_e32 v20, v20
	v_rcp_f32_e32 v22, v22
	v_rcp_f32_e32 v21, v21
	v_rcp_f32_e32 v23, v23
	v_rcp_f32_e32 v24, v24
	v_rcp_f32_e32 v26, v26
	v_rcp_f32_e32 v25, v25
	v_rcp_f32_e32 v27, v27
	v_add_u32_e32 v18, 0xb0, v158
	v_pk_mul_f32 v[8:9], v[16:17], v[8:9]
	v_pk_mul_f32 v[6:7], v[14:15], v[6:7]
	v_pk_mul_f32 v[4:5], v[12:13], v[4:5]
	v_pk_mul_f32 v[2:3], v[10:11], v[2:3]
	v_mad_i64_i32 v[18:19], s[40:41], v18, s38, v[140:141]
	v_pk_mul_f32 v[8:9], v[24:25], v[8:9]
	v_pk_mul_f32 v[6:7], v[20:21], v[6:7]
	v_pk_mul_f32 v[10:11], v[26:27], v[4:5]
	v_pk_mul_f32 v[4:5], v[22:23], v[2:3]
	v_lshl_add_u64 v[18:19], v[18:19], 0, v[142:143]
	v_cvt_pk_bf16_f32 v2, v6, v7
	v_cvt_pk_bf16_f32 v3, v8, v9
	v_cvt_pk_bf16_f32 v4, v4, v5
	v_cvt_pk_bf16_f32 v5, v10, v11
	s_andn2_b64 vcc, exec, s[4:5]
	s_mov_b64 s[4:5], -1
	global_store_dwordx4 v[18:19], v[2:5], off
	s_cbranch_vccnz .LBB0_509
	s_andn2_b64 vcc, exec, s[6:7]
	s_cbranch_vccnz .LBB0_508
	s_barrier
	s_branch .LBB0_508
